# blocking unit admission: up to 8 quick counter re-polls (no unit decode / clock read) per outer poll iteration
# speedup vs baseline: 1.0058x; 1.0011x over previous
.LBB0_201:
	s_or_b64 exec, exec, s[34:35]
	v_cmp_ne_u64_e32 vcc, 0, v[132:133]
	s_waitcnt lgkmcnt(0)
	s_mov_b64 s[6:7], -1
	s_and_saveexec_b64 s[34:35], vcc
	s_cbranch_execz .LBB0_203
	s_movk_i32 s98, 8
.Ladm_repoll:
	global_load_dword v112, v[132:133], off sc1
	s_waitcnt vmcnt(0)
	v_cmp_ge_u32_e32 vcc, v112, v141
	s_cmp_eq_u64 vcc, exec
	s_cbranch_scc1 .Ladm_polled
	s_sub_u32 s98, s98, 1
	s_cmp_eq_u32 s98, 0
	s_cbranch_scc1 .Ladm_polled
	s_sleep 1
	s_branch .Ladm_repoll
.Ladm_polled:
	s_orn2_b64 s[6:7], vcc, exec
